# GEMM1: in rounds 2 and 5 the two XCD parities swap N halves so every workgroup gets at most 3 tiles with silu/sigmoid epilogues (was 1 vs 4-5)
# baseline (speedup 1.0000x reference)
.LBB0_275:
	s_cmp_lt_u32 s14, 48
	s_cbranch_scc0 .Lp1_noswap
	s_cmp_eq_u32 s41, 2
	s_cbranch_scc1 .Lp1_swap
	s_cmp_eq_u32 s41, 5
	s_cbranch_scc0 .Lp1_noswap
.Lp1_swap:
	s_add_i32 s14, s14, 24
	s_sub_i32 s13, s14, 48
	s_cmp_ge_u32 s14, 48
	s_cselect_b32 s14, s13, s14
